# same as the G1-tail weight conversion version plus a guard: phase 0 converts all layers itself when the grid is not 256 workgroups
# speedup vs baseline: 1.0186x; 1.0013x over previous
; #define LAS __attribute__((address_space(3)))
; __global__ void __launch_bounds__(NTHR, 2) mega_fwd(Args args) {
;     extern __shared__ __attribute__((aligned(16))) unsigned char lds_raw[];
;     LAS unsigned char* lds = (LAS unsigned char*)lds_raw;
;     cg::grid_group grid = cg::this_grid();
;     volatile LAS unsigned* bst = (volatile LAS unsigned*)(lds + LDS_BYTES - 64);
;     if (threadIdx.x < 16) bst[threadIdx.x] = 0u;
;     __syncthreads();
;     XcdBarrier xbar = xcd_barrier_post((unsigned*)(args.ws + WS_BAR), bst);
_Z8mega_fwd4Args:
	s_load_dwordx8 s[24:31], s[0:1], 0xa0
	s_mov_b32 s100, 0
	s_load_dwordx8 s[4:11], s[0:1], 0x80
	s_load_dwordx2 s[90:91], s[0:1], 0xc0
	s_mov_b32 s89, s2
	s_add_u32 s2, s0, 0xc0
	s_addc_u32 s3, s1, 0
	s_waitcnt lgkmcnt(0)
	s_mov_b32 s101, 0x102ff
	s_cmpk_eq_u32 s90, 0x100
	s_cselect_b32 s101, 0x40bf, s101
	v_writelane_b32 v251, s4, 0
	v_and_b32_e32 v141, 0x3ff, v0
	v_cmp_gt_u32_e32 vcc, 16, v141
	v_writelane_b32 v251, s5, 1
	v_writelane_b32 v251, s6, 2
	v_writelane_b32 v251, s7, 3
	v_writelane_b32 v251, s8, 4
	v_writelane_b32 v251, s9, 5
	v_writelane_b32 v251, s10, 6
	v_writelane_b32 v251, s11, 7
	v_writelane_b32 v251, s2, 8
	s_nop 1
	v_writelane_b32 v251, s3, 9
	s_and_saveexec_b64 s[2:3], vcc
	v_lshl_add_u32 v1, v141, 2, 0
	v_add_u32_e32 v1, 0x23fc0, v1
	v_mov_b32_e32 v2, 0
	ds_write_b32 v1, v2
	s_or_b64 exec, exec, s[2:3]
	s_waitcnt lgkmcnt(0)
	s_barrier
	s_add_u32 s2, s28, 0xc00000
	s_getreg_b32 s4, hwreg(HW_REG_XCC_ID, 0, 4)
	s_addc_u32 s3, s29, 0
	s_and_b32 s6, s4, 15
	v_cmp_eq_u32_e64 s[68:69], 0, v141
	s_and_saveexec_b64 s[4:5], s[68:69]
	s_cbranch_execz .LBB0_5
	s_mov_b64 s[8:9], exec
	v_mbcnt_lo_u32_b32 v1, s8, 0
	v_mbcnt_hi_u32_b32 v1, s9, v1
	v_cmp_eq_u32_e32 vcc, 0, v1
	s_and_b64 s[10:11], exec, vcc
	s_mov_b64 exec, s[10:11]
	s_cbranch_execz .LBB0_5
	s_lshl_b32 s7, s6, 8
	s_bcnt1_i32_b64 s8, s[8:9]
	v_mov_b32_e32 v1, s7
	v_mov_b32_e32 v2, s8
	global_atomic_add v1, v2, s[2:3] offset:1024
